# gdn_chunk forward substitution: eight rows' x_j and coefficient LDS reads issued per batch (was one LDS round trip per row), plain v_fma_f32 instead of v_pk_fma_f32
# speedup vs baseline: 1.0381x; 1.0107x over previous
; DI void gdn_chunk(CP c, int l, int item, float* sm) {
;     ...
; #pragma unroll 8
;             for (int j = 0; j < i0; ++j) { const float xj = R[j * 260 + col]; const f32x4 la = *(const f32x4*)(Ls + j * 68 + i0), lb = *(const f32x4*)(Ls + j * 68 + i0 + 4);
;                 acc[0] -= la[0] * xj; acc[1] -= la[1] * xj; acc[2] -= la[2] * xj; acc[3] -= la[3] * xj;
;                 acc[4] -= lb[0] * xj; acc[5] -= lb[1] * xj; acc[6] -= lb[2] * xj; acc[7] -= lb[3] * xj; }
.LBB0_960:
	v_add_u32_e32 v13, 0x10800, v12
	s_add_i32 s0, s12, 0x20c00
	v_mov_b32_e32 v14, s0
	ds_read_b32 v64, v13
	ds_read_b32 v65, v13 offset:1040
	ds_read_b32 v66, v13 offset:2080
	ds_read_b32 v67, v13 offset:3120
	ds_read_b32 v70, v13 offset:4160
	ds_read_b32 v71, v13 offset:5200
	ds_read_b32 v72, v13 offset:6240
	ds_read_b32 v73, v13 offset:7280
	ds_read_b128 v[42:45], v14
	ds_read_b128 v[46:49], v14 offset:16
	ds_read_b128 v[50:53], v14 offset:272
	ds_read_b128 v[54:57], v14 offset:288
	ds_read_b128 v[58:61], v14 offset:544
	ds_read_b128 v[74:77], v14 offset:560
	ds_read_b128 v[84:87], v14 offset:816
	ds_read_b128 v[88:91], v14 offset:832
	ds_read_b128 v[124:127], v14 offset:1088
	ds_read_b128 v[128:131], v14 offset:1104
	ds_read_b128 v[132:135], v14 offset:1360
	ds_read_b128 v[136:139], v14 offset:1376
	ds_read_b128 v[140:143], v14 offset:1632
	ds_read_b128 v[144:147], v14 offset:1648
	ds_read_b128 v[148:151], v14 offset:1904
	ds_read_b128 v[152:155], v14 offset:1920
	s_addk_i32 s12, 0x880
	v_add_u32_e32 v12, 0x2080, v12
	s_add_i32 s13, s13, -8
	s_waitcnt lgkmcnt(14)
	v_fma_f32 v2, -v64, v42, v2
	v_fma_f32 v3, -v64, v43, v3
	v_fma_f32 v8, -v64, v44, v8
	v_fma_f32 v9, -v64, v45, v9
	v_fma_f32 v6, -v64, v46, v6
	v_fma_f32 v7, -v64, v47, v7
	v_fma_f32 v4, -v64, v48, v4
	v_fma_f32 v5, -v64, v49, v5
	s_waitcnt lgkmcnt(12)
	v_fma_f32 v2, -v65, v50, v2
	v_fma_f32 v3, -v65, v51, v3
	v_fma_f32 v8, -v65, v52, v8
	v_fma_f32 v9, -v65, v53, v9
	v_fma_f32 v6, -v65, v54, v6
	v_fma_f32 v7, -v65, v55, v7
	v_fma_f32 v4, -v65, v56, v4
	v_fma_f32 v5, -v65, v57, v5
	s_waitcnt lgkmcnt(10)
	v_fma_f32 v2, -v66, v58, v2
	v_fma_f32 v3, -v66, v59, v3
	v_fma_f32 v8, -v66, v60, v8
	v_fma_f32 v9, -v66, v61, v9
	v_fma_f32 v6, -v66, v74, v6
	v_fma_f32 v7, -v66, v75, v7
	v_fma_f32 v4, -v66, v76, v4
	v_fma_f32 v5, -v66, v77, v5
	s_waitcnt lgkmcnt(8)
	v_fma_f32 v2, -v67, v84, v2
	v_fma_f32 v3, -v67, v85, v3
	v_fma_f32 v8, -v67, v86, v8
	v_fma_f32 v9, -v67, v87, v9
	v_fma_f32 v6, -v67, v88, v6
	v_fma_f32 v7, -v67, v89, v7
	v_fma_f32 v4, -v67, v90, v4
	v_fma_f32 v5, -v67, v91, v5
	s_waitcnt lgkmcnt(6)
	v_fma_f32 v2, -v70, v124, v2
	v_fma_f32 v3, -v70, v125, v3
	v_fma_f32 v8, -v70, v126, v8
	v_fma_f32 v9, -v70, v127, v9
	v_fma_f32 v6, -v70, v128, v6
	v_fma_f32 v7, -v70, v129, v7
	v_fma_f32 v4, -v70, v130, v4
	v_fma_f32 v5, -v70, v131, v5
	s_waitcnt lgkmcnt(4)
	v_fma_f32 v2, -v71, v132, v2
	v_fma_f32 v3, -v71, v133, v3
	v_fma_f32 v8, -v71, v134, v8
	v_fma_f32 v9, -v71, v135, v9
	v_fma_f32 v6, -v71, v136, v6
	v_fma_f32 v7, -v71, v137, v7
	v_fma_f32 v4, -v71, v138, v4
	v_fma_f32 v5, -v71, v139, v5
	s_waitcnt lgkmcnt(2)
	v_fma_f32 v2, -v72, v140, v2
	v_fma_f32 v3, -v72, v141, v3
	v_fma_f32 v8, -v72, v142, v8
	v_fma_f32 v9, -v72, v143, v9
	v_fma_f32 v6, -v72, v144, v6
	v_fma_f32 v7, -v72, v145, v7
	v_fma_f32 v4, -v72, v146, v4
	v_fma_f32 v5, -v72, v147, v5
	s_waitcnt lgkmcnt(0)
	v_fma_f32 v2, -v73, v148, v2
	v_fma_f32 v3, -v73, v149, v3
	v_fma_f32 v8, -v73, v150, v8
	v_fma_f32 v9, -v73, v151, v9
	v_fma_f32 v6, -v73, v152, v6
	v_fma_f32 v7, -v73, v153, v7
	v_fma_f32 v4, -v73, v154, v4
	v_fma_f32 v5, -v73, v155, v5
	s_cmp_eq_u32 s13, 0
	s_cbranch_scc0 .LBB0_960
	s_branch .LBB0_958
